# v16 plus sg_w conversion loop (workgroup G-2) batched 32 loads deep instead of 16
# baseline (speedup 1.0000x reference)
; __device__ __forceinline__ unsigned cvtpk(float lo, float hi) { f32x2 v = {lo, hi}; bf16x2_t b = __builtin_convertvector(v, bf16x2_t); return __builtin_bit_cast(unsigned, b); }
; __device__ __forceinline__ void p0_prologue(const Args& a, LAS unsigned char* lds, int tid, int wid, int lane, int G) {
;     ...
;     } else if ((int)blockIdx.x == G - 2) {
;         bf16_t* sw = (bf16_t*)(ws + WS_SGW);
;         for (int i = tid; i < 8 * 128 * 128 / 2; i += 512) ((unsigned*)sw)[i] = cvtpk(a.sg_w[2 * i], a.sg_w[2 * i + 1]);
.LBB0_17:
	v_and_b32_e32 v177, 63, v176
	s_cmpk_gt_i32 s2, 0xbf
	s_mov_b64 s[4:5], -1
	s_cbranch_scc0 .LBB0_37
	s_add_i32 s3, s30, -1
	s_cmp_lg_u32 s2, s3
	s_cbranch_scc0 .LBB0_24
	s_add_i32 s3, s30, -2
	s_cmp_lg_u32 s2, s3
	s_cbranch_scc1 .LBB0_23
	v_lshlrev_b32_e32 v2, 2, v176
	v_mov_b32_e32 v3, 0
	v_lshl_add_u64 v[0:1], s[28:29], 0, v[2:3]
	s_mov_b64 s[4:5], 0x90000
	v_lshlrev_b32_e32 v2, 3, v176
	v_add_u32_e32 v4, 0xfffffe00, v176
	v_lshl_add_u64 v[0:1], v[0:1], 0, s[4:5]
	v_lshl_add_u64 v[2:3], s[44:45], 0, v[2:3]
	s_mov_b64 s[4:5], 0
	s_mov_b64 s[8:9], 0x800
	s_mov_b64 s[10:11], 0x1000
	s_mov_b32 s3, 0xfdff
	s_movk_i32 s3, 4
; __device__ __forceinline__ unsigned cvtpk(float lo, float hi) { f32x2 v = {lo, hi}; bf16x2_t b = __builtin_convertvector(v, bf16x2_t); return __builtin_bit_cast(unsigned, b); }
; __device__ __forceinline__ void p0_prologue(const Args& a, LAS unsigned char* lds, int tid, int wid, int lane, int G) {
;     ...
;     } else if ((int)blockIdx.x == G - 2) {
;         bf16_t* sw = (bf16_t*)(ws + WS_SGW);
;         for (int i = tid; i < 8 * 128 * 128 / 2; i += 512) ((unsigned*)sw)[i] = cvtpk(a.sg_w[2 * i], a.sg_w[2 * i + 1]);
.Lsgw_loop:
	global_load_dwordx2 v[128:129], v[2:3], off
	v_lshl_add_u64 v[2:3], v[2:3], 0, s[10:11]
	global_load_dwordx2 v[130:131], v[2:3], off
	v_lshl_add_u64 v[2:3], v[2:3], 0, s[10:11]
	global_load_dwordx2 v[132:133], v[2:3], off
	v_lshl_add_u64 v[2:3], v[2:3], 0, s[10:11]
	global_load_dwordx2 v[134:135], v[2:3], off
	v_lshl_add_u64 v[2:3], v[2:3], 0, s[10:11]
	global_load_dwordx2 v[136:137], v[2:3], off
	v_lshl_add_u64 v[2:3], v[2:3], 0, s[10:11]
	global_load_dwordx2 v[138:139], v[2:3], off
	v_lshl_add_u64 v[2:3], v[2:3], 0, s[10:11]
	global_load_dwordx2 v[140:141], v[2:3], off
	v_lshl_add_u64 v[2:3], v[2:3], 0, s[10:11]
	global_load_dwordx2 v[142:143], v[2:3], off
	v_lshl_add_u64 v[2:3], v[2:3], 0, s[10:11]
	global_load_dwordx2 v[144:145], v[2:3], off
	v_lshl_add_u64 v[2:3], v[2:3], 0, s[10:11]
	global_load_dwordx2 v[146:147], v[2:3], off
	v_lshl_add_u64 v[2:3], v[2:3], 0, s[10:11]
	global_load_dwordx2 v[148:149], v[2:3], off
	v_lshl_add_u64 v[2:3], v[2:3], 0, s[10:11]
	global_load_dwordx2 v[150:151], v[2:3], off
	v_lshl_add_u64 v[2:3], v[2:3], 0, s[10:11]
	global_load_dwordx2 v[152:153], v[2:3], off
	v_lshl_add_u64 v[2:3], v[2:3], 0, s[10:11]
	global_load_dwordx2 v[154:155], v[2:3], off
	v_lshl_add_u64 v[2:3], v[2:3], 0, s[10:11]
	global_load_dwordx2 v[156:157], v[2:3], off
	v_lshl_add_u64 v[2:3], v[2:3], 0, s[10:11]
	global_load_dwordx2 v[158:159], v[2:3], off
	v_lshl_add_u64 v[2:3], v[2:3], 0, s[10:11]
	global_load_dwordx2 v[160:161], v[2:3], off
	v_lshl_add_u64 v[2:3], v[2:3], 0, s[10:11]
	global_load_dwordx2 v[162:163], v[2:3], off
	v_lshl_add_u64 v[2:3], v[2:3], 0, s[10:11]
	global_load_dwordx2 v[166:167], v[2:3], off
	v_lshl_add_u64 v[2:3], v[2:3], 0, s[10:11]
	global_load_dwordx2 v[168:169], v[2:3], off
	v_lshl_add_u64 v[2:3], v[2:3], 0, s[10:11]
	global_load_dwordx2 v[170:171], v[2:3], off
	v_lshl_add_u64 v[2:3], v[2:3], 0, s[10:11]
	global_load_dwordx2 v[172:173], v[2:3], off
	v_lshl_add_u64 v[2:3], v[2:3], 0, s[10:11]
	global_load_dwordx2 v[174:175], v[2:3], off
	v_lshl_add_u64 v[2:3], v[2:3], 0, s[10:11]
	global_load_dwordx2 v[178:179], v[2:3], off
	v_lshl_add_u64 v[2:3], v[2:3], 0, s[10:11]
	global_load_dwordx2 v[180:181], v[2:3], off
	v_lshl_add_u64 v[2:3], v[2:3], 0, s[10:11]
	global_load_dwordx2 v[184:185], v[2:3], off
	v_lshl_add_u64 v[2:3], v[2:3], 0, s[10:11]
	global_load_dwordx2 v[186:187], v[2:3], off
	v_lshl_add_u64 v[2:3], v[2:3], 0, s[10:11]
	global_load_dwordx2 v[188:189], v[2:3], off
	v_lshl_add_u64 v[2:3], v[2:3], 0, s[10:11]
	global_load_dwordx2 v[190:191], v[2:3], off
	v_lshl_add_u64 v[2:3], v[2:3], 0, s[10:11]
	global_load_dwordx2 v[192:193], v[2:3], off
	v_lshl_add_u64 v[2:3], v[2:3], 0, s[10:11]
	global_load_dwordx2 v[194:195], v[2:3], off
	v_lshl_add_u64 v[2:3], v[2:3], 0, s[10:11]
	global_load_dwordx2 v[232:233], v[2:3], off
	v_lshl_add_u64 v[2:3], v[2:3], 0, s[10:11]
	s_waitcnt vmcnt(0)
	v_cvt_pk_bf16_f32 v200, v128, v129
	v_cvt_pk_bf16_f32 v201, v130, v131
	v_cvt_pk_bf16_f32 v202, v132, v133
	v_cvt_pk_bf16_f32 v203, v134, v135
	v_cvt_pk_bf16_f32 v204, v136, v137
	v_cvt_pk_bf16_f32 v205, v138, v139
	v_cvt_pk_bf16_f32 v206, v140, v141
	v_cvt_pk_bf16_f32 v207, v142, v143
	v_cvt_pk_bf16_f32 v208, v144, v145
	v_cvt_pk_bf16_f32 v209, v146, v147
	v_cvt_pk_bf16_f32 v210, v148, v149
	v_cvt_pk_bf16_f32 v211, v150, v151
	v_cvt_pk_bf16_f32 v212, v152, v153
	v_cvt_pk_bf16_f32 v213, v154, v155
	v_cvt_pk_bf16_f32 v214, v156, v157
	v_cvt_pk_bf16_f32 v215, v158, v159
	v_cvt_pk_bf16_f32 v216, v160, v161
	v_cvt_pk_bf16_f32 v217, v162, v163
	v_cvt_pk_bf16_f32 v218, v166, v167
	v_cvt_pk_bf16_f32 v219, v168, v169
	v_cvt_pk_bf16_f32 v220, v170, v171
	v_cvt_pk_bf16_f32 v221, v172, v173
	v_cvt_pk_bf16_f32 v222, v174, v175
	v_cvt_pk_bf16_f32 v223, v178, v179
	v_cvt_pk_bf16_f32 v224, v180, v181
	v_cvt_pk_bf16_f32 v225, v184, v185
	v_cvt_pk_bf16_f32 v226, v186, v187
	v_cvt_pk_bf16_f32 v227, v188, v189
	v_cvt_pk_bf16_f32 v228, v190, v191
	v_cvt_pk_bf16_f32 v229, v192, v193
	v_cvt_pk_bf16_f32 v230, v194, v195
	v_cvt_pk_bf16_f32 v231, v232, v233
	global_store_dword v[0:1], v200, off
	v_lshl_add_u64 v[0:1], v[0:1], 0, s[8:9]
	global_store_dword v[0:1], v201, off
	v_lshl_add_u64 v[0:1], v[0:1], 0, s[8:9]
	global_store_dword v[0:1], v202, off
	v_lshl_add_u64 v[0:1], v[0:1], 0, s[8:9]
	global_store_dword v[0:1], v203, off
	v_lshl_add_u64 v[0:1], v[0:1], 0, s[8:9]
	global_store_dword v[0:1], v204, off
	v_lshl_add_u64 v[0:1], v[0:1], 0, s[8:9]
	global_store_dword v[0:1], v205, off
	v_lshl_add_u64 v[0:1], v[0:1], 0, s[8:9]
	global_store_dword v[0:1], v206, off
	v_lshl_add_u64 v[0:1], v[0:1], 0, s[8:9]
	global_store_dword v[0:1], v207, off
	v_lshl_add_u64 v[0:1], v[0:1], 0, s[8:9]
	global_store_dword v[0:1], v208, off
	v_lshl_add_u64 v[0:1], v[0:1], 0, s[8:9]
	global_store_dword v[0:1], v209, off
	v_lshl_add_u64 v[0:1], v[0:1], 0, s[8:9]
	global_store_dword v[0:1], v210, off
	v_lshl_add_u64 v[0:1], v[0:1], 0, s[8:9]
	global_store_dword v[0:1], v211, off
	v_lshl_add_u64 v[0:1], v[0:1], 0, s[8:9]
	global_store_dword v[0:1], v212, off
	v_lshl_add_u64 v[0:1], v[0:1], 0, s[8:9]
	global_store_dword v[0:1], v213, off
	v_lshl_add_u64 v[0:1], v[0:1], 0, s[8:9]
	global_store_dword v[0:1], v214, off
	v_lshl_add_u64 v[0:1], v[0:1], 0, s[8:9]
	global_store_dword v[0:1], v215, off
	v_lshl_add_u64 v[0:1], v[0:1], 0, s[8:9]
	global_store_dword v[0:1], v216, off
	v_lshl_add_u64 v[0:1], v[0:1], 0, s[8:9]
	global_store_dword v[0:1], v217, off
	v_lshl_add_u64 v[0:1], v[0:1], 0, s[8:9]
	global_store_dword v[0:1], v218, off
	v_lshl_add_u64 v[0:1], v[0:1], 0, s[8:9]
	global_store_dword v[0:1], v219, off
	v_lshl_add_u64 v[0:1], v[0:1], 0, s[8:9]
	global_store_dword v[0:1], v220, off
	v_lshl_add_u64 v[0:1], v[0:1], 0, s[8:9]
	global_store_dword v[0:1], v221, off
	v_lshl_add_u64 v[0:1], v[0:1], 0, s[8:9]
	global_store_dword v[0:1], v222, off
	v_lshl_add_u64 v[0:1], v[0:1], 0, s[8:9]
	global_store_dword v[0:1], v223, off
	v_lshl_add_u64 v[0:1], v[0:1], 0, s[8:9]
	global_store_dword v[0:1], v224, off
	v_lshl_add_u64 v[0:1], v[0:1], 0, s[8:9]
	global_store_dword v[0:1], v225, off
	v_lshl_add_u64 v[0:1], v[0:1], 0, s[8:9]
	global_store_dword v[0:1], v226, off
	v_lshl_add_u64 v[0:1], v[0:1], 0, s[8:9]
	global_store_dword v[0:1], v227, off
	v_lshl_add_u64 v[0:1], v[0:1], 0, s[8:9]
	global_store_dword v[0:1], v228, off
	v_lshl_add_u64 v[0:1], v[0:1], 0, s[8:9]
	global_store_dword v[0:1], v229, off
	v_lshl_add_u64 v[0:1], v[0:1], 0, s[8:9]
	global_store_dword v[0:1], v230, off
	v_lshl_add_u64 v[0:1], v[0:1], 0, s[8:9]
	global_store_dword v[0:1], v231, off
	v_lshl_add_u64 v[0:1], v[0:1], 0, s[8:9]
	s_add_i32 s3, s3, -1
	s_cmp_lg_u32 s3, 0
	s_cbranch_scc1 .Lsgw_loop
	s_or_b64 exec, exec, s[4:5]
